# mixers: second WG of each CU (nonzero LDS base) walks its NA items before its MLA items (rounds 1,2,3,0) to co-schedule MLA with NA on a CU
# speedup vs baseline: 1.0039x; 1.0039x over previous
.LBB0_208:
	v_readlane_b32 s20, v221, 61
	v_readlane_b32 s0, v225, 42
	v_readlane_b32 s1, v225, 43
	s_load_dword s0, s[0:1], 0x0
	s_waitcnt lgkmcnt(0)
	s_add_i32 s20, s0, s20
	s_cmp_ge_i32 s20, s27
	s_cbranch_scc1 .LBB0_306
.LBB0_209:
	v_writelane_b32 v221, s20, 61
	s_movk_i32 s1, 0x800
	s_movk_i32 s0, 0xfa00
	s_cmpk_lt_u32 s20, 0x800
	s_cselect_b32 s1, s1, s0
	s_movk_i32 s0, 0xf200
	s_cmpk_ge_u32 s20, 0xe00
	s_cselect_b32 s1, s0, s1
	s_cmpk_lt_u32 s20, 0x1000
	s_cselect_b32 s1, s1, 0
	s_getreg_b32 s0, hwreg(HW_REG_LDS_ALLOC, 0, 8)
	s_cmp_lg_u32 s0, 0
	s_cselect_b32 s1, s1, 0
	s_add_i32 s20, s20, s1
	s_cmp_ge_i32 s20, s14
	s_mov_b64 s[0:1], -1
	s_cbranch_scc0 .LBB0_211
	s_sub_i32 s0, s20, s14
	s_lshl_b32 s0, s0, 5
	v_mov_b32_e32 v10, v196
	s_and_b32 s2, s0, 0x7fffff80
	s_and_b32 s5, s20, 3
	v_lshrrev_b32_e32 v0, 2, v10
	s_lshl_b64 s[0:1], s[2:3], 10
	v_and_b32_e32 v0, 12, v0
	s_add_u32 s2, s15, s0
	v_lshrrev_b32_e64 v0, v0, s57
	s_addc_u32 s7, s21, s1
	s_lshl_b32 s4, s5, 8
	v_xor_b32_e32 v0, v0, v10
	s_add_u32 s6, s2, s4
	v_ashrrev_i32_e32 v2, 2, v10
	v_lshlrev_b32_e32 v0, 4, v0
	s_addc_u32 s7, s7, 0
	v_and_b32_e32 v0, 48, v0
	v_ashrrev_i32_e32 v3, 31, v2
	v_lshl_add_u64 v[4:5], s[6:7], 0, v[0:1]
	v_lshlrev_b64 v[6:7], 10, v[2:3]
	v_lshl_add_u64 v[70:71], v[4:5], 0, v[6:7]
	v_add_u32_e32 v6, 64, v2
	s_lshl_b32 s2, s5, 15
	v_readlane_b32 s8, v224, 11
	v_ashrrev_i32_e32 v7, 31, v6
	s_add_u32 s8, s8, s2
	v_readlane_b32 s2, v224, 12
	v_lshlrev_b64 v[8:9], 10, v[6:7]
	s_addc_u32 s9, s2, 0
	v_lshl_add_u64 v[72:73], v[4:5], 0, v[8:9]
	v_and_b32_e32 v8, 15, v10
	v_lshlrev_b64 v[4:5], 8, v[6:7]
	v_lshl_add_u32 v12, v10, 4, 0
	v_lshrrev_b32_e32 v6, 1, v10
	s_mov_b32 s2, 0x3ffffc0
	v_lshlrev_b64 v[2:3], 8, v[2:3]
	v_and_or_b32 v13, v6, s2, v8
	v_readfirstlane_b32 s2, v12
	v_add_u32_e32 v8, 0x1000, v12
	v_lshl_add_u64 v[2:3], s[8:9], 0, v[2:3]
	v_and_b32_e32 v6, 12, v10
	s_mov_b32 m0, s2
	v_readfirstlane_b32 s6, v8
	v_lshl_add_u64 v[74:75], v[2:3], 0, v[0:1]
	v_add_u32_e32 v2, 0x2000, v12
	v_lshrrev_b32_e32 v11, 4, v10
	v_lshl_add_u64 v[4:5], s[8:9], 0, v[4:5]
	v_lshrrev_b32_e64 v6, v6, s57
	global_load_lds_dwordx4 v[70:71], off
	s_mov_b32 m0, s6
	v_readfirstlane_b32 s7, v2
	v_add_u32_e32 v2, 0x3000, v12
	v_xor_b32_e32 v6, v6, v11
	global_load_lds_dwordx4 v[72:73], off
	v_lshl_add_u64 v[76:77], v[4:5], 0, v[0:1]
	s_mov_b32 m0, s7
	v_readfirstlane_b32 s8, v2
	v_add_u32_e32 v4, 0x4000, v12
	v_lshlrev_b32_e32 v11, 4, v6
	v_lshlrev_b32_e32 v6, 6, v10
	global_load_lds_dwordx4 v[74:75], off
	s_mov_b32 m0, s8
	v_readfirstlane_b32 s9, v4
	v_and_b32_e32 v10, 0x13c0, v6
	v_lshl_add_u64 v[6:7], v[70:71], 0, 64
	global_load_lds_dwordx4 v[76:77], off
	s_mov_b32 m0, s9
	v_add_u32_e32 v4, 0x5000, v12
	global_load_lds_dwordx4 v[6:7], off
	v_readfirstlane_b32 s9, v4
	v_add_u32_e32 v6, 0x6000, v12
	v_lshl_add_u64 v[8:9], v[72:73], 0, 64
	s_mov_b32 m0, s9
	v_readfirstlane_b32 s9, v6
	v_lshl_add_u64 v[2:3], v[74:75], 0, 64
	global_load_lds_dwordx4 v[8:9], off
	s_mov_b32 m0, s9
	v_and_b32_e32 v0, 48, v11
	global_load_lds_dwordx4 v[2:3], off
	v_add_u32_e32 v2, 0x7000, v12
	v_lshl_add_u64 v[4:5], v[76:77], 0, 64
	v_readfirstlane_b32 s9, v2
	s_mov_b32 m0, s9
	v_add_u32_e32 v11, 0x8000, v12
	global_load_lds_dwordx4 v[4:5], off
	v_add_u32_e32 v14, 0xb000, v12
	v_add_u32_e32 v15, 0xa000, v12
	v_add_u32_e32 v12, 0x9000, v12
	v_readfirstlane_b32 s9, v11
	s_waitcnt vmcnt(4) lgkmcnt(0)
	s_barrier
	v_lshl_add_u64 v[2:3], v[70:71], 0, s[78:79]
	s_mov_b32 m0, s9
	v_readfirstlane_b32 s9, v12
	v_lshl_add_u64 v[4:5], v[72:73], 0, s[78:79]
	global_load_lds_dwordx4 v[2:3], off
	s_mov_b32 m0, s9
	v_readfirstlane_b32 s9, v15
	v_lshl_add_u64 v[8:9], v[74:75], 0, s[78:79]
	global_load_lds_dwordx4 v[4:5], off
	s_mov_b32 m0, s9
	v_readfirstlane_b32 s9, v14
	v_lshl_add_u64 v[6:7], v[76:77], 0, s[78:79]
	global_load_lds_dwordx4 v[8:9], off
	s_mov_b32 m0, s9
	v_add3_u32 v90, 0, v10, v0
	v_lshlrev_b32_e32 v10, 6, v13
	global_load_lds_dwordx4 v[6:7], off
	v_add3_u32 v0, 0, v10, v0
	ds_read_b128 v[2:5], v90 offset:8192
	ds_read_b128 v[6:9], v90 offset:9216
	ds_read_b128 v[10:13], v0
	ds_read_b128 v[14:17], v0 offset:1024
	ds_read_b128 v[22:25], v90 offset:10240
	ds_read_b128 v[30:33], v90 offset:11264
	ds_read_b128 v[50:53], v0 offset:2048
	ds_read_b128 v[54:57], v0 offset:3072
	v_lshl_add_u64 v[70:71], v[70:71], 0, s[84:85]
	s_waitcnt vmcnt(4) lgkmcnt(0)
	s_barrier
	s_mov_b32 m0, s2
	v_lshl_add_u64 v[72:73], v[72:73], 0, s[84:85]
	global_load_lds_dwordx4 v[70:71], off
	s_mov_b32 m0, s6
	v_lshl_add_u64 v[74:75], v[74:75], 0, s[84:85]
	global_load_lds_dwordx4 v[72:73], off
	s_mov_b32 m0, s7
	v_lshl_add_u64 v[76:77], v[76:77], 0, s[84:85]
	global_load_lds_dwordx4 v[74:75], off
	s_mov_b32 m0, s8
	s_waitcnt lgkmcnt(0)
	s_setprio 1
	v_mfma_f32_16x16x32_bf16 v[18:21], v[2:5], v[10:13], 0
	global_load_lds_dwordx4 v[76:77], off
	s_setprio 0
	ds_read_b128 v[70:73], v90 offset:24576
	s_setprio 1
	v_mfma_f32_16x16x32_bf16 v[26:29], v[6:9], v[10:13], 0
	s_lshl_b32 s2, s5, 9
	v_lshl_add_u64 v[94:95], v[146:147], 0, s[2:3]
	v_readlane_b32 s2, v224, 1
	v_mfma_f32_16x16x32_bf16 v[34:37], v[22:25], v[10:13], 0
	s_add_u32 s0, s2, s0
	v_readlane_b32 s2, v224, 2
	s_addc_u32 s1, s2, s1
	v_mfma_f32_16x16x32_bf16 v[10:13], v[30:33], v[10:13], 0
	s_mov_b32 s2, 0xfffffc0
	s_add_u32 s0, s0, s4
	s_addc_u32 s1, s1, 0
	v_mfma_f32_16x16x32_bf16 v[38:41], v[2:5], v[14:17], 0
	v_mfma_f32_16x16x32_bf16 v[42:45], v[6:9], v[14:17], 0
	v_mfma_f32_16x16x32_bf16 v[46:49], v[22:25], v[14:17], 0
	v_mfma_f32_16x16x32_bf16 v[14:17], v[30:33], v[14:17], 0
	v_mfma_f32_16x16x32_bf16 v[58:61], v[2:5], v[50:53], 0
	v_mfma_f32_16x16x32_bf16 v[62:65], v[6:9], v[50:53], 0
	v_mfma_f32_16x16x32_bf16 v[66:69], v[22:25], v[50:53], 0
	v_mfma_f32_16x16x32_bf16 v[50:53], v[30:33], v[50:53], 0
	v_mfma_f32_16x16x32_bf16 v[2:5], v[2:5], v[54:57], 0
	v_mfma_f32_16x16x32_bf16 v[6:9], v[6:9], v[54:57], 0
	v_mfma_f32_16x16x32_bf16 v[22:25], v[22:25], v[54:57], 0
	v_mfma_f32_16x16x32_bf16 v[30:33], v[30:33], v[54:57], 0
	s_setprio 0
	ds_read_b128 v[54:57], v90 offset:25600
	ds_read_b128 v[74:77], v0 offset:16384
	ds_read_b128 v[78:81], v0 offset:17408
	ds_read_b128 v[82:85], v90 offset:26624
	ds_read_b128 v[86:89], v90 offset:27648
	s_waitcnt lgkmcnt(0)
	s_setprio 1
	v_mfma_f32_16x16x32_bf16 v[18:21], v[70:73], v[74:77], v[18:21]
	v_mfma_f32_16x16x32_bf16 v[26:29], v[54:57], v[74:77], v[26:29]
	v_mfma_f32_16x16x32_bf16 v[34:37], v[82:85], v[74:77], v[34:37]
	v_mfma_f32_16x16x32_bf16 v[10:13], v[86:89], v[74:77], v[10:13]
	v_mfma_f32_16x16x32_bf16 v[38:41], v[70:73], v[78:81], v[38:41]
	v_mfma_f32_16x16x32_bf16 v[42:45], v[54:57], v[78:81], v[42:45]
	v_mfma_f32_16x16x32_bf16 v[46:49], v[82:85], v[78:81], v[46:49]
	v_mfma_f32_16x16x32_bf16 v[14:17], v[86:89], v[78:81], v[14:17]
	s_setprio 0
	ds_read_b128 v[74:77], v0 offset:18432
	ds_read_b128 v[78:81], v0 offset:19456
	s_waitcnt vmcnt(4) lgkmcnt(0)
	s_barrier
	s_waitcnt lgkmcnt(0)
	s_setprio 1
	v_mfma_f32_16x16x32_bf16 v[58:61], v[70:73], v[74:77], v[58:61]
	v_mfma_f32_16x16x32_bf16 v[62:65], v[54:57], v[74:77], v[62:65]
	v_mfma_f32_16x16x32_bf16 v[66:69], v[82:85], v[74:77], v[66:69]
	v_mfma_f32_16x16x32_bf16 v[50:53], v[86:89], v[74:77], v[50:53]
	v_mfma_f32_16x16x32_bf16 v[2:5], v[70:73], v[78:81], v[2:5]
	v_mfma_f32_16x16x32_bf16 v[6:9], v[54:57], v[78:81], v[6:9]
	s_setprio 0
	ds_read_b128 v[54:57], v90 offset:40960
	s_setprio 1
	v_mfma_f32_16x16x32_bf16 v[22:25], v[82:85], v[78:81], v[22:25]
	v_mfma_f32_16x16x32_bf16 v[30:33], v[86:89], v[78:81], v[30:33]
	s_setprio 0
	ds_read_b128 v[70:73], v90 offset:41984
	ds_read_b128 v[74:77], v0 offset:32768
	ds_read_b128 v[78:81], v0 offset:33792
	ds_read_b128 v[82:85], v90 offset:43008
	ds_read_b128 v[86:89], v90 offset:44032
	s_waitcnt lgkmcnt(0)
	s_setprio 1
	v_mfma_f32_16x16x32_bf16 v[18:21], v[54:57], v[74:77], v[18:21]
	v_mfma_f32_16x16x32_bf16 v[26:29], v[70:73], v[74:77], v[26:29]
	v_mfma_f32_16x16x32_bf16 v[34:37], v[82:85], v[74:77], v[34:37]
	v_mfma_f32_16x16x32_bf16 v[10:13], v[86:89], v[74:77], v[10:13]
	v_mfma_f32_16x16x32_bf16 v[38:41], v[54:57], v[78:81], v[38:41]
	v_mfma_f32_16x16x32_bf16 v[42:45], v[70:73], v[78:81], v[42:45]
	v_mfma_f32_16x16x32_bf16 v[46:49], v[82:85], v[78:81], v[46:49]
	v_mfma_f32_16x16x32_bf16 v[14:17], v[86:89], v[78:81], v[14:17]
	s_setprio 0
	ds_read_b128 v[74:77], v0 offset:34816
	ds_read_b128 v[78:81], v0 offset:35840
	s_waitcnt vmcnt(0) lgkmcnt(0)
	s_barrier
	s_waitcnt lgkmcnt(0)
	s_setprio 1
	v_mfma_f32_16x16x32_bf16 v[58:61], v[54:57], v[74:77], v[58:61]
	v_mfma_f32_16x16x32_bf16 v[62:65], v[70:73], v[74:77], v[62:65]
	v_mfma_f32_16x16x32_bf16 v[66:69], v[82:85], v[74:77], v[66:69]
	v_mfma_f32_16x16x32_bf16 v[50:53], v[86:89], v[74:77], v[50:53]
	v_mfma_f32_16x16x32_bf16 v[2:5], v[54:57], v[78:81], v[2:5]
	s_setprio 0
	ds_read_b128 v[54:57], v90 offset:8192
	s_setprio 1
	v_mfma_f32_16x16x32_bf16 v[6:9], v[70:73], v[78:81], v[6:9]
	v_mfma_f32_16x16x32_bf16 v[22:25], v[82:85], v[78:81], v[22:25]
	v_mfma_f32_16x16x32_bf16 v[30:33], v[86:89], v[78:81], v[30:33]
	s_setprio 0
	ds_read_b128 v[70:73], v90 offset:9216
	ds_read_b128 v[74:77], v0
	ds_read_b128 v[78:81], v0 offset:1024
	ds_read_b128 v[82:85], v90 offset:10240
	ds_read_b128 v[86:89], v90 offset:11264
	s_waitcnt lgkmcnt(0)
	s_setprio 1
	v_mfma_f32_16x16x32_bf16 v[18:21], v[54:57], v[74:77], v[18:21]
	v_mfma_f32_16x16x32_bf16 v[26:29], v[70:73], v[74:77], v[26:29]
	v_mfma_f32_16x16x32_bf16 v[34:37], v[82:85], v[74:77], v[34:37]
	v_mfma_f32_16x16x32_bf16 v[10:13], v[86:89], v[74:77], v[10:13]
	v_mfma_f32_16x16x32_bf16 v[38:41], v[54:57], v[78:81], v[38:41]
	v_mfma_f32_16x16x32_bf16 v[42:45], v[70:73], v[78:81], v[42:45]
	v_mfma_f32_16x16x32_bf16 v[46:49], v[82:85], v[78:81], v[46:49]
	v_mfma_f32_16x16x32_bf16 v[14:17], v[86:89], v[78:81], v[14:17]
	s_setprio 0
	ds_read_b128 v[74:77], v0 offset:2048
	ds_read_b128 v[78:81], v0 offset:3072
	s_waitcnt vmcnt(0) lgkmcnt(0)
	s_barrier
	s_setprio 1
	v_mfma_f32_16x16x32_bf16 v[58:61], v[54:57], v[74:77], v[58:61]
	global_load_dwordx4 v[90:93], v[94:95], off
	v_mfma_f32_16x16x32_bf16 v[2:5], v[54:57], v[78:81], v[2:5]
	global_load_dwordx4 v[54:57], v[94:95], off offset:128
	v_mfma_f32_16x16x32_bf16 v[62:65], v[70:73], v[74:77], v[62:65]
	v_mfma_f32_16x16x32_bf16 v[66:69], v[82:85], v[74:77], v[66:69]
	v_mfma_f32_16x16x32_bf16 v[50:53], v[86:89], v[74:77], v[50:53]
	global_load_dwordx4 v[74:77], v[94:95], off offset:64
	s_setprio 0
	s_waitcnt vmcnt(2)
	v_pk_mul_f32 v[18:19], v[18:19], v[90:91]
	s_setprio 1
	v_mfma_f32_16x16x32_bf16 v[6:9], v[70:73], v[78:81], v[6:9]
	global_load_dwordx4 v[70:73], v[94:95], off offset:192
	s_setprio 0
	s_waitcnt vmcnt(2)
	v_pk_mul_f32 v[34:35], v[34:35], v[54:55]
	v_pk_mul_f32 v[46:47], v[46:47], v[54:55]
	s_setprio 1
	v_mfma_f32_16x16x32_bf16 v[22:25], v[82:85], v[78:81], v[22:25]
	v_mul_f32_e64 v66, v66, v54
	v_mul_f32_e64 v67, v67, v55
	v_pk_mul_f32 v[36:37], v[36:37], v[56:57]
	v_pk_mul_f32 v[48:49], v[48:49], v[56:57]
	v_mfma_f32_16x16x32_bf16 v[30:33], v[86:89], v[78:81], v[30:33]
	v_mul_f32_e64 v20, v20, v92
	v_mul_f32_e64 v21, v21, v93
	s_nop 0
	v_pk_mul_f32 v[22:23], v[22:23], v[54:55]
	v_pk_mul_f32 v[54:55], v[68:69], v[56:57]
	v_pk_mul_f32 v[24:25], v[24:25], v[56:57]
	v_mov_b32_e32 v56, v196
	s_setprio 0
	s_waitcnt vmcnt(1)
	v_pk_mul_f32 v[26:27], v[26:27], v[74:75]
	v_and_b32_e32 v57, 15, v56
	v_lshrrev_b32_e32 v68, 1, v56
	v_and_b32_e32 v0, 64, v56
	v_and_or_b32 v69, v68, s2, v57
	v_pk_mul_f32 v[28:29], v[28:29], v[76:77]
	v_lshl_add_u32 v0, v0, 1, 0
	v_and_b32_e32 v68, 24, v68
	v_mul_lo_u32 v69, v69, s30
	v_add3_u32 v0, v0, v68, v69
	v_cvt_pk_bf16_f32 v18, v18, v19
	v_cvt_pk_bf16_f32 v19, v20, v21
	v_cvt_pk_bf16_f32 v20, v26, v27
	v_cvt_pk_bf16_f32 v21, v28, v29
	v_pk_mul_f32 v[38:39], v[38:39], v[90:91]
	v_pk_mul_f32 v[40:41], v[40:41], v[92:93]
	v_pk_mul_f32 v[42:43], v[42:43], v[74:75]
	v_pk_mul_f32 v[44:45], v[44:45], v[76:77]
	ds_write2_b64 v0, v[18:19], v[20:21] offset1:4
	v_cvt_pk_bf16_f32 v18, v34, v35
	v_cvt_pk_bf16_f32 v19, v36, v37
	v_pk_mul_f32 v[2:3], v[2:3], v[90:91]
	v_pk_mul_f32 v[4:5], v[4:5], v[92:93]
	v_pk_mul_f32 v[6:7], v[6:7], v[74:75]
	v_pk_mul_f32 v[8:9], v[8:9], v[76:77]
	v_pk_mul_f32 v[58:59], v[58:59], v[90:91]
	v_pk_mul_f32 v[60:61], v[60:61], v[92:93]
	v_pk_mul_f32 v[62:63], v[62:63], v[74:75]
	v_pk_mul_f32 v[64:65], v[64:65], v[76:77]
	v_cvt_pk_bf16_f32 v2, v2, v3
	v_cvt_pk_bf16_f32 v3, v4, v5
	v_cvt_pk_bf16_f32 v4, v6, v7
	v_cvt_pk_bf16_f32 v5, v8, v9
	v_add_u32_e32 v6, 0x100, v56
	s_waitcnt vmcnt(0)
	v_pk_mul_f32 v[10:11], v[10:11], v[70:71]
	v_pk_mul_f32 v[12:13], v[12:13], v[72:73]
	v_cvt_pk_bf16_f32 v10, v10, v11
	v_cvt_pk_bf16_f32 v11, v12, v13
	v_pk_mul_f32 v[14:15], v[14:15], v[70:71]
	v_pk_mul_f32 v[16:17], v[16:17], v[72:73]
	ds_write2_b64 v0, v[18:19], v[10:11] offset0:8 offset1:12
	v_cvt_pk_bf16_f32 v10, v38, v39
	v_cvt_pk_bf16_f32 v11, v40, v41
	v_cvt_pk_bf16_f32 v12, v42, v43
	v_cvt_pk_bf16_f32 v13, v44, v45
	v_add_u32_e32 v18, 0x1000, v0
	v_pk_mul_f32 v[30:31], v[30:31], v[70:71]
	v_pk_mul_f32 v[32:33], v[32:33], v[72:73]
	ds_write2_b64 v18, v[10:11], v[12:13] offset0:32 offset1:36
	v_cvt_pk_bf16_f32 v10, v46, v47
	v_cvt_pk_bf16_f32 v11, v48, v49
	v_cvt_pk_bf16_f32 v12, v14, v15
	v_cvt_pk_bf16_f32 v13, v16, v17
	v_add_u32_e32 v14, 0x2000, v0
	v_add_u32_e32 v0, 0x3000, v0
	v_pk_mul_f32 v[50:51], v[50:51], v[70:71]
	v_pk_mul_f32 v[52:53], v[52:53], v[72:73]
	ds_write2_b64 v18, v[10:11], v[12:13] offset0:40 offset1:44
	v_cvt_pk_bf16_f32 v10, v58, v59
	v_cvt_pk_bf16_f32 v11, v60, v61
	v_cvt_pk_bf16_f32 v12, v62, v63
	v_cvt_pk_bf16_f32 v13, v64, v65
	ds_write2_b64 v0, v[2:3], v[4:5] offset0:96 offset1:100
	v_cvt_pk_bf16_f32 v2, v22, v23
	v_cvt_pk_bf16_f32 v3, v24, v25
	v_cvt_pk_bf16_f32 v4, v30, v31
	v_cvt_pk_bf16_f32 v5, v32, v33
	ds_write2_b64 v14, v[10:11], v[12:13] offset0:64 offset1:68
	v_cvt_pk_bf16_f32 v10, v66, v67
	v_cvt_pk_bf16_f32 v11, v54, v55
	v_cvt_pk_bf16_f32 v12, v50, v51
	v_cvt_pk_bf16_f32 v13, v52, v53
	ds_write2_b64 v0, v[2:3], v[4:5] offset0:104 offset1:108
	v_lshlrev_b32_e32 v0, 4, v57
	v_ashrrev_i32_e32 v2, 4, v56
	ds_write2_b64 v14, v[10:11], v[12:13] offset0:72 offset1:76
	v_lshl_add_u64 v[10:11], s[0:1], 0, v[0:1]
	v_add_u32_e32 v0, 0, v0
	v_ashrrev_i32_e32 v3, 31, v2
	v_mad_u64_u32 v[4:5], s[0:1], v2, s30, v[0:1]
	v_lshlrev_b64 v[2:3], 10, v[2:3]
	s_waitcnt lgkmcnt(0)
	s_barrier
	v_lshl_add_u64 v[12:13], v[10:11], 0, v[2:3]
	ds_read_b128 v[2:5], v4
	v_ashrrev_i32_e32 v14, 4, v6
	v_mad_u64_u32 v[6:7], s[0:1], v14, s30, v[0:1]
	ds_read_b128 v[6:9], v6
	v_ashrrev_i32_e32 v15, 31, v14
	s_waitcnt lgkmcnt(1)
	global_store_dwordx4 v[12:13], v[2:5], off
	s_nop 1
	v_lshlrev_b64 v[2:3], 10, v[14:15]
	v_lshl_add_u64 v[2:3], v[10:11], 0, v[2:3]
	s_waitcnt lgkmcnt(0)
	global_store_dwordx4 v[2:3], v[6:9], off
	v_add_u32_e32 v2, 0x200, v56
	v_ashrrev_i32_e32 v2, 4, v2
	v_ashrrev_i32_e32 v3, 31, v2
	v_mad_u64_u32 v[4:5], s[0:1], v2, s30, v[0:1]
	v_lshlrev_b64 v[2:3], 10, v[2:3]
	v_add_u32_e32 v6, 0x300, v56
	v_lshl_add_u64 v[12:13], v[10:11], 0, v[2:3]
	ds_read_b128 v[2:5], v4
	v_ashrrev_i32_e32 v14, 4, v6
	v_mad_u64_u32 v[6:7], s[0:1], v14, s30, v[0:1]
	ds_read_b128 v[6:9], v6
	v_ashrrev_i32_e32 v15, 31, v14
	s_waitcnt lgkmcnt(1)
	global_store_dwordx4 v[12:13], v[2:5], off
	s_nop 1
	v_lshlrev_b64 v[2:3], 10, v[14:15]
	v_lshl_add_u64 v[2:3], v[10:11], 0, v[2:3]
	s_waitcnt lgkmcnt(0)
	global_store_dwordx4 v[2:3], v[6:9], off
	v_add_u32_e32 v2, 0x400, v56
	v_ashrrev_i32_e32 v2, 4, v2
	v_ashrrev_i32_e32 v3, 31, v2
	v_mad_u64_u32 v[4:5], s[0:1], v2, s30, v[0:1]
	v_lshlrev_b64 v[2:3], 10, v[2:3]
	v_add_u32_e32 v6, 0x500, v56
	v_lshl_add_u64 v[12:13], v[10:11], 0, v[2:3]
	ds_read_b128 v[2:5], v4
	v_ashrrev_i32_e32 v14, 4, v6
	v_mad_u64_u32 v[6:7], s[0:1], v14, s30, v[0:1]
	ds_read_b128 v[6:9], v6
	v_ashrrev_i32_e32 v15, 31, v14
	s_waitcnt lgkmcnt(1)
	global_store_dwordx4 v[12:13], v[2:5], off
	s_nop 1
	v_lshlrev_b64 v[2:3], 10, v[14:15]
	v_lshl_add_u64 v[2:3], v[10:11], 0, v[2:3]
	s_waitcnt lgkmcnt(0)
	global_store_dwordx4 v[2:3], v[6:9], off
	v_add_u32_e32 v2, 0x600, v56
	v_ashrrev_i32_e32 v2, 4, v2
	v_ashrrev_i32_e32 v3, 31, v2
	v_mad_u64_u32 v[4:5], s[0:1], v2, s30, v[0:1]
	v_lshlrev_b64 v[2:3], 10, v[2:3]
	v_add_u32_e32 v6, 0x700, v56
	v_lshl_add_u64 v[12:13], v[10:11], 0, v[2:3]
	ds_read_b128 v[2:5], v4
	v_ashrrev_i32_e32 v14, 4, v6
	v_mad_u64_u32 v[6:7], s[0:1], v14, s30, v[0:1]
	ds_read_b128 v[6:9], v6
	v_ashrrev_i32_e32 v15, 31, v14
	s_waitcnt lgkmcnt(1)
	global_store_dwordx4 v[12:13], v[2:5], off
	s_mov_b64 s[0:1], 0
	s_nop 0
	v_lshlrev_b64 v[2:3], 10, v[14:15]
	v_lshl_add_u64 v[2:3], v[10:11], 0, v[2:3]
	s_waitcnt lgkmcnt(0)
	global_store_dwordx4 v[2:3], v[6:9], off
	s_barrier
